# combined: CP_STATIC 9, one-round-trip bias-table copy in PA/SA prologues, PA K/V chunk L2-touch prefetch (distance 2)
# baseline (speedup 1.0000x reference)
.LBB0_483:
	s_and_b64 vcc, exec, s[0:1]
	s_cbranch_vccz .LBB0_598
	s_and_b32 s0, s5, 0xffff
	s_mul_i32 s0, s0, 0xaaab
	s_lshr_b32 s39, s0, 21
	s_mul_i32 s0, s39, 48
	s_sub_i32 s0, s5, s0
	s_and_b32 s1, s0, 0xff
	s_mulk_i32 s1, 0xab
	s_load_dwordx4 s[12:15], s[52:53], 0x80
	s_bfe_u32 s2, s1, 0x5000b
	s_mul_i32 s3, s2, 12
	v_mov_b32_e32 v4, v0
	s_sub_i32 s0, s0, s3
	s_sub_i32 s42, 7, s39
	v_readfirstlane_b32 s40, v4
	s_and_b32 s44, s0, 0xff
	s_ashr_i32 s66, s40, 6
	s_mov_b64 s[6:7], 0
	s_waitcnt lgkmcnt(0)
	s_add_u32 s36, s12, s6
	s_addc_u32 s37, s13, s7
	s_add_u32 s68, s36, 0x4c00000
	v_and_b32_e32 v212, 31, v4
	s_addc_u32 s69, s37, 0
	s_lshl_b32 s41, s42, 8
	s_and_b32 s0, s1, 0xf800
	s_or_b32 s5, s0, s41
	v_lshlrev_b32_e32 v3, 3, v212
	v_or_b32_e32 v5, s5, v3
	v_add_u32_e32 v5, s66, v5
	v_mov_b64_e32 v[6:7], s[68:69]
	v_mad_i64_i32 v[6:7], s[0:1], v5, s19, v[6:7]
	v_bfe_u32 v211, v4, 5, 1
	s_lshl_b32 s0, s44, 8
	s_mov_b32 s1, s21
	v_lshl_add_u64 v[6:7], v[6:7], 0, s[0:1]
	v_lshlrev_b32_e32 v198, 4, v211
	v_mov_b32_e32 v199, v2
	v_lshl_add_u64 v[6:7], v[6:7], 0, v[198:199]
	s_lshl_b32 s43, s66, 2
	v_bfe_u32 v197, v4, 4, 2
	global_load_dwordx4 v[162:165], v[6:7], off
	global_load_dwordx4 v[166:169], v[6:7], off offset:32
	global_load_dwordx4 v[170:173], v[6:7], off offset:64
	global_load_dwordx4 v[174:177], v[6:7], off offset:96
	global_load_dwordx4 v[178:181], v[6:7], off offset:128
	global_load_dwordx4 v[182:185], v[6:7], off offset:160
	global_load_dwordx4 v[186:189], v[6:7], off offset:192
	global_load_dwordx4 v[190:193], v[6:7], off offset:224
	v_or_b32_e32 v5, s43, v197
	v_lshlrev_b32_e32 v6, 4, v4
	v_and_b32_e32 v6, 0xf0, v6
	v_lshlrev_b32_e32 v7, 4, v5
	s_movk_i32 s0, 0x70
	v_bitop3_b32 v6, v7, v6, s0 bitop3:0x6c
	s_ashr_i32 s1, s40, 4
	v_lshrrev_b32_e32 v8, 1, v6
	s_and_b32 s3, s1, 0x3ffffff0
	v_lshrrev_b32_e32 v6, 2, v4
	v_lshrrev_b32_e32 v199, 1, v4
	s_lshr_b32 s1, s1, 1
	s_lshl_b32 s0, s66, 1
	v_and_or_b32 v6, v6, 3, s3
	v_and_b32_e32 v7, 8, v199
	s_and_b32 s1, s1, 4
	s_lshl_b32 s20, s44, 7
	v_or3_b32 v6, v6, v7, s1
	v_and_or_b32 v7, s0, 2, v211
	v_lshlrev_b32_e32 v210, 3, v4
	v_lshlrev_b32_e32 v7, 5, v7
	v_and_b32_e32 v9, 24, v210
	s_add_i32 s0, s20, 0xc00
	s_ashr_i32 s67, s66, 31
	v_lshlrev_b32_e32 v10, 2, v6
	v_or3_b32 v6, v7, v9, s0
	v_mov_b32_e32 v7, v2
	s_movk_i32 s3, 0x1800
	s_mul_i32 s2, s2, 0x1800000
	v_mad_i64_i32 v[200:201], s[0:1], v10, s3, v[6:7]
	s_add_u32 s70, s68, s2
	v_lshlrev_b32_e32 v5, 2, v5
	s_addc_u32 s71, s69, 0
	s_lshl_b32 s0, s66, 10
	v_mov_b64_e32 v[6:7], s[20:21]
	s_add_i32 s38, s0, 0
	v_mad_i64_i32 v[202:203], s[0:1], v5, s3, v[6:7]
	v_or_b32_e32 v202, v202, v8
	v_lshl_add_u64 v[6:7], v[202:203], 1, s[70:71]
	s_mov_b64 s[0:1], 0xc00
	v_lshl_add_u64 v[8:9], v[6:7], 0, s[0:1]
	s_add_i32 s0, s38, 0x8000
	s_mov_b32 m0, s38
	v_lshl_add_u64 v[10:11], v[200:201], 1, s[70:71]
	global_load_lds_dwordx4 v[8:9], off
	s_mov_b32 m0, s0
	s_mov_b64 s[0:1], 0x3c00
	global_load_lds_dwordx4 v[10:11], off
	v_lshl_add_u64 v[8:9], v[6:7], 0, s[0:1]
	s_add_i32 m0, s38, 0x2000
	s_mov_b64 s[0:1], 0x3000
	global_load_lds_dwordx4 v[8:9], off
	v_lshl_add_u64 v[8:9], v[10:11], 0, s[0:1]
	s_add_i32 m0, s38, 0xa000
	s_mov_b64 s[0:1], 0x6c00
	global_load_lds_dwordx4 v[8:9], off
	v_lshl_add_u64 v[8:9], v[6:7], 0, s[0:1]
	s_add_i32 m0, s38, 0x4000
	s_mov_b64 s[0:1], 0x6000
	global_load_lds_dwordx4 v[8:9], off
	v_lshl_add_u64 v[8:9], v[10:11], 0, s[0:1]
	s_add_i32 m0, s38, 0xc000
	s_mov_b64 s[0:1], 0x9c00
	global_load_lds_dwordx4 v[8:9], off
	v_lshl_add_u64 v[6:7], v[6:7], 0, s[0:1]
	s_add_i32 m0, s38, 0x6000
	s_mov_b64 s[0:1], 0x9000
	global_load_lds_dwordx4 v[6:7], off
	v_lshl_add_u64 v[6:7], v[10:11], 0, s[0:1]
	s_add_i32 m0, s38, 0xe000
	s_movk_i32 s0, 0xa80
	global_load_lds_dwordx4 v[6:7], off
	v_lshrrev_b32_e32 v250, 2, v0
	v_bfe_u32 v251, v0, 1, 1
	v_mul_u32_u24_e32 v250, 0x3000, v250
	v_mul_u32_u24_e32 v251, 0xc00, v251
	s_lshl_b32 s2, s20, 1
	v_add_u32_e32 v250, v250, v251
	v_and_b32_e32 v251, 1, v0
	s_addk_i32 s2, 0xc00
	v_lshlrev_b32_e32 v251, 7, v251
	v_add_u32_e32 v250, s2, v250
	v_add_u32_e32 v250, v250, v251
	s_mul_i32 s2, s44, 0x2a00
	s_add_u32 s2, s36, s2
	s_addc_u32 s3, s37, 0
	s_add_u32 s2, s2, 0x2900000
	s_addc_u32 s3, s3, 0
	v_lshlrev_b32_e32 v108, 4, v0
	v_add_u32_e32 v109, 0x2000, v108
	global_load_dwordx4 v[100:103], v108, s[2:3]
	v_cmp_gt_u32_e32 vcc, 0xa0, v0
	s_and_saveexec_b64 s[12:13], vcc
	global_load_dwordx4 v[104:107], v109, s[2:3]
	s_or_b64 exec, exec, s[12:13]
	v_and_b32_e32 v213, 63, v4
	v_lshlrev_b32_e32 v4, 3, v213
	v_lshlrev_b32_e32 v6, 4, v213
	s_and_b32 s0, s40, 0x3fffffc0
	v_and_b32_e32 v5, 24, v4
	v_and_b32_e32 v6, 0xc0, v6
	v_lshlrev_b32_e32 v8, 1, v213
	s_lshl_b32 s0, s0, 2
	v_or_b32_e32 v7, v5, v6
	v_and_b32_e32 v8, 32, v8
	v_and_b32_e32 v4, 0x100, v4
	s_add_i32 s2, s0, 0
	v_or3_b32 v214, v7, v8, v4
	v_lshlrev_b32_e32 v7, 4, v212
	s_movk_i32 s0, 0x70
	v_and_b32_e32 v9, 0x70, v7
	v_bitop3_b32 v216, v198, v7, s0 bitop3:0x78
	s_movk_i32 s0, 0x60
	v_bitop3_b32 v219, v198, v9, s0 bitop3:0x36
	s_movk_i32 s0, 0x80
	v_bitop3_b32 v220, v198, v9, s0 bitop3:0x36
	s_movk_i32 s0, 0xa0
	v_bitop3_b32 v221, v198, v9, s0 bitop3:0x36
	s_movk_i32 s0, 0xc0
	v_bitop3_b32 v223, v198, v9, s0 bitop3:0x36
	s_movk_i32 s0, 0xe0
	v_bitop3_b32 v224, v198, v9, s0 bitop3:0x36
	s_add_i32 s0, s41, s66
	s_addk_i32 s0, 0x180
	v_add_u32_e32 v225, s0, v3
	v_lshl_add_u32 v3, v212, 5, s43
	v_lshlrev_b32_e32 v16, 6, v211
	v_sub_u32_e32 v3, v3, v16
	s_lshl_b32 s0, s39, 10
	v_subrev_u32_e32 v226, s0, v3
	s_add_i32 s0, 0, 0x8000
	s_waitcnt vmcnt(0)
	v_add_u32_e32 v108, s51, v108
	ds_write_b128 v108, v[100:103]
	v_cmp_gt_u32_e32 vcc, 0xa0, v0
	s_and_saveexec_b64 vcc, vcc
	ds_write_b128 v108, v[104:107] offset:8192
	s_mov_b64 exec, vcc
	v_lshlrev_b32_e32 v215, 8, v212
	v_or_b32_e32 v7, 32, v198
	v_or_b32_e32 v10, 64, v198
	v_or_b32_e32 v11, 0x60, v198
	v_or_b32_e32 v12, 0x80, v198
	v_or_b32_e32 v13, 0xa0, v198
	v_or_b32_e32 v14, 0xc0, v198
	v_or_b32_e32 v15, 0xe0, v198
	v_add3_u32 v3, v4, s0, v6
	v_mov_b32_e32 v16, v2
	v_mov_b32_e32 v17, v2
	s_lshl_b32 s12, s42, 1
	s_add_i32 s2, s2, 0x22a00
	v_bitop3_b32 v217, v198, v9, 32 bitop3:0x36
	v_bitop3_b32 v218, v198, v9, 64 bitop3:0x36
	s_bfe_u32 s13, s40, 0x20006
	v_add3_u32 v227, v3, v8, v5
	v_bitop3_b32 v228, v198, v215, v9 bitop3:0xde
	v_bitop3_b32 v229, v7, v215, v9 bitop3:0xde
	v_bitop3_b32 v230, v10, v215, v9 bitop3:0xde
	v_bitop3_b32 v231, v11, v215, v9 bitop3:0xde
	v_bitop3_b32 v232, v12, v215, v9 bitop3:0xde
	v_bitop3_b32 v233, v13, v215, v9 bitop3:0xde
	v_bitop3_b32 v234, v15, v215, v9 bitop3:0xde
	v_bitop3_b32 v235, v14, v215, v9 bitop3:0xde
	v_mov_b32_e32 v3, v2
	v_mov_b32_e32 v4, v2
	v_mov_b32_e32 v5, v2
	v_mov_b32_e32 v6, v2
	v_mov_b32_e32 v7, v2
	v_mov_b32_e32 v8, v2
	v_mov_b32_e32 v9, v2
	v_mov_b32_e32 v10, v2
	v_mov_b32_e32 v11, v2
	v_mov_b32_e32 v12, v2
	v_mov_b32_e32 v13, v2
	v_mov_b32_e32 v14, v2
	v_mov_b32_e32 v15, v2
	v_mov_b64_e32 v[32:33], v[16:17]
	v_mov_b64_e32 v[48:49], v[16:17]
	v_mov_b64_e32 v[64:65], v[16:17]
	v_mov_b64_e32 v[80:81], v[16:17]
	s_add_i32 s3, s12, 2
	s_add_i32 s12, s12, -1
	v_cmp_gt_u32_e64 s[6:7], 32, v213
	v_lshl_add_u32 v222, v212, 2, s2
	s_lshl_b32 s14, s13, 13
	s_mov_b32 s15, 0
	v_mov_b32_e32 v237, 0xe0ad78ec
	v_mov_b32_e32 v236, 0
	v_mov_b64_e32 v[30:31], v[14:15]
	v_mov_b64_e32 v[28:29], v[12:13]
	v_mov_b64_e32 v[26:27], v[10:11]
	v_mov_b64_e32 v[24:25], v[8:9]
	v_mov_b64_e32 v[22:23], v[6:7]
	v_mov_b64_e32 v[20:21], v[4:5]
	v_mov_b64_e32 v[18:19], v[2:3]
	v_mov_b64_e32 v[46:47], v[14:15]
	v_mov_b64_e32 v[44:45], v[12:13]
	v_mov_b64_e32 v[42:43], v[10:11]
	v_mov_b64_e32 v[40:41], v[8:9]
	v_mov_b64_e32 v[38:39], v[6:7]
	v_mov_b64_e32 v[36:37], v[4:5]
	v_mov_b64_e32 v[34:35], v[2:3]
	v_mov_b64_e32 v[62:63], v[14:15]
	v_mov_b64_e32 v[60:61], v[12:13]
	v_mov_b64_e32 v[58:59], v[10:11]
	v_mov_b64_e32 v[56:57], v[8:9]
	v_mov_b64_e32 v[54:55], v[6:7]
	v_mov_b64_e32 v[52:53], v[4:5]
	v_mov_b64_e32 v[50:51], v[2:3]
	v_mov_b64_e32 v[78:79], v[14:15]
	v_mov_b64_e32 v[76:77], v[12:13]
	v_mov_b64_e32 v[74:75], v[10:11]
	v_mov_b64_e32 v[72:73], v[8:9]
	v_mov_b64_e32 v[70:71], v[6:7]
	v_mov_b64_e32 v[68:69], v[4:5]
	v_mov_b64_e32 v[66:67], v[2:3]
	s_mov_b32 s25, 0
	s_waitcnt vmcnt(0) lgkmcnt(0)
	s_barrier
	s_add_i32 s24, s25, 1
	s_cmp_ge_u32 s24, s3
	s_cbranch_scc0 .LBB0_499
	s_branch .LBB0_500
